# differential-attention loop: all 8 K-fragment LDS reads issued right after the barrier, tile staging writes moved ahead of the bf16 packing
# baseline (speedup 1.0000x reference)
; #define LAS __attribute__((address_space(3)))
; #define MFMA32(a, b, c) __builtin_amdgcn_mfma_f32_32x32x16_bf16((a), (b), (c), 0, 0, 0)
; #define LOAD_TILE(t) do { const size_t _tb = (size_t)TILE_ROW(t); rk0 = *(const u32x4*)(Kp + (_tb + kr0) * ldk + kc0 * 8); \
;         if (hask1) rk1 = *(const u32x4*)(Kp + (_tb + kr1) * ldk + kc1 * 8); rv = *(const u32x4*)(Vp + (_tb + vr) * ldv + vc * 8); } while (0)
; #define STORE_TILE(buf) do { LAS unsigned char* _kb = lds + (buf) * BUFSZ; *(LAS u32x4*)(_kb + kr0 * KSTR + kc0 * 16) = rk0; \
;         if (hask1) *(LAS u32x4*)(_kb + kr1 * KSTR + kc1 * 16) = rk1; *(LAS u32x4*)(_kb + KBUF + vr * VSTR + vc * 16) = rv; } while (0)
; template <int MODE>
; __device__ __forceinline__ void attn_item(PK p, int l, LAS unsigned char* lds, int b, int h, int qb, bool ctxq, float lam, float lam_init) {
;     ...
;     for (int t = 0; t < nt; ++t) {
;         const bool more = (t + 1 < nt);
;         if (more) LOAD_TILE(t + 1);
;         bool active = true; int krow = 0;
;         if (nabias && t < nloc) { krow = loc0 + t; active = (krow >= sw) && (krow < sw + 8); }
;         bool slow = (MODE == 0) || (t == 0);
;         if (active) {
;           again:
;             LAS unsigned char* Kb = lds + cbuf * BUFSZ + koff;
;             f32x16 S[NCOMP][2];
; #pragma unroll
;             for (int c = 0; c < NCOMP; ++c)
; #pragma unroll
;                 for (int kt = 0; kt < 2; ++kt) {
;                     bf16x8 kf[NKS];
; #pragma unroll
;                     for (int ks = 0; ks < NKS; ++ks) kf[ks] = *(const LAS bf16x8*)(Kb + kt * 32 * KSTR + (c * NKS + ks) * 32);
; #pragma unroll
;                     for (int r = 0; r < 16; ++r) S[c][kt][r] = 0.f;
;                     __builtin_amdgcn_s_setprio(1);
; #pragma unroll
;                     for (int ks = 0; ks < NKS; ++ks) S[c][kt] = MFMA32(kf[ks], qf[c * NKS + ks], S[c][kt]);
;                     __builtin_amdgcn_s_setprio(0);
;                 }
;     ...
;         const int nbuf = (cbuf == 2) ? 0 : cbuf + 1;
;         if (more) STORE_TILE(nbuf);
.LBB0_265:
	s_add_i32 s18, s0, 1
	s_cmpk_lt_u32 s0, 0x83
	s_cselect_b64 s[8:9], -1, 0
	s_cmp_eq_u32 s0, 0
	s_cselect_b64 s[10:11], -1, 0
	s_mov_b64 s[12:13], s[10:11]
	s_mul_i32 s1, s17, 0x5400
	v_add_u32_e32 v239, s1, v205
	ds_read_b128 v[72:75], v239
	ds_read_b128 v[76:79], v239 offset:32
	ds_read_b128 v[80:83], v239 offset:4608
	ds_read_b128 v[222:225], v239 offset:4640
	ds_read_b128 v[226:229], v239 offset:64
	ds_read_b128 v[246:249], v239 offset:96
	ds_read_b128 v[68:71], v239 offset:4672
	ds_read_b128 v[190:193], v239 offset:4704
	s_cmpk_gt_u32 s0, 0x82
	s_cbranch_scc1 .Ldiff_mfma
	s_cmpk_lt_u32 s0, 0x7f
	s_cselect_b32 s1, 0, 0xffffff80
	s_cselect_b32 s4, s6, s7
	s_add_i32 s1, s1, s18
	s_lshl_b32 s1, s1, 6
	s_add_i32 s88, s1, s4
	v_lshl_add_u64 v[2:3], s[88:89], 0, v[208:209]
	v_mad_u64_u32 v[250:251], s[4:5], v2, s56, v[210:211]
	v_mad_i32_i24 v251, v3, s56, v251
	v_lshl_add_u64 v[2:3], s[88:89], 0, v[206:207]
	v_mad_u64_u32 v[252:253], s[4:5], v2, s56, v[212:213]
	v_mad_i32_i24 v253, v3, s56, v253
	global_load_dwordx4 v[132:135], v[250:251], off
	global_load_dwordx4 v[136:139], v[252:253], off
	s_branch .Ldiff_mfma
.LBB0_268:
	s_andn2_b64 vcc, exec, s[8:9]
	s_cbranch_vccnz .Ldiff_skip_st
	s_add_i32 s0, s17, 1
	s_cmp_lg_u32 s17, 2
	s_cselect_b32 s0, s0, 0
	s_mul_i32 s0, s0, 0x5400
	v_add3_u32 v218, s0, v233, v234
	v_add3_u32 v219, s0, v235, v204
	s_waitcnt vmcnt(1)
	ds_write_b128 v218, v[132:135]
	s_waitcnt vmcnt(0)
	ds_write_b128 v219, v[136:139] offset:9216

; #define LAS __attribute__((address_space(3)))
; #define MFMA32(a, b, c) __builtin_amdgcn_mfma_f32_32x32x16_bf16((a), (b), (c), 0, 0, 0)
; template <int MODE>
; __device__ __forceinline__ void attn_item(PK p, int l, LAS unsigned char* lds, int b, int h, int qb, bool ctxq, float lam, float lam_init) {
;     ...
;           again:
;             LAS unsigned char* Kb = lds + cbuf * BUFSZ + koff;
;             f32x16 S[NCOMP][2];
; #pragma unroll
;             for (int c = 0; c < NCOMP; ++c)
; #pragma unroll
;                 for (int kt = 0; kt < 2; ++kt) {
;                     bf16x8 kf[NKS];
; #pragma unroll
;                     for (int ks = 0; ks < NKS; ++ks) kf[ks] = *(const LAS bf16x8*)(Kb + kt * 32 * KSTR + (c * NKS + ks) * 32);
; #pragma unroll
;                     for (int r = 0; r < 16; ++r) S[c][kt][r] = 0.f;
;                     __builtin_amdgcn_s_setprio(1);
; #pragma unroll
;                     for (int ks = 0; ks < NKS; ++ks) S[c][kt] = MFMA32(kf[ks], qf[c * NKS + ks], S[c][kt]);
;                     __builtin_amdgcn_s_setprio(0);
;                 }
;             if (STAG && late && pend) { PV_TILE(pbuf); pend = false; }
;             float mxc[NCOMP], mnw[NCOMP];
;             if (!slow) {
; #pragma unroll
;                 for (int c = 0; c < NCOMP; ++c) mnw[c] = mrun[c];
;             } else {
; #pragma unroll
;             for (int c = 0; c < NCOMP; ++c) {
;                 float mx = -1e30f;
;                 if (nabias && t < nloc) {
;                     const LAS float* bt = (const LAS float*)(lds + BIAS_OFF) + (krow - rw + 7) * 31;
; #pragma unroll
;                     for (int kt = 0; kt < 2; ++kt)
; #pragma unroll
;                         for (int r = 0; r < 16; ++r) { const int jk = 32 * kt + (r & 3) + 8 * (r >> 2) + 4 * g; const bool ok = (jk >= cst) && (jk < cst + 16);
;                             const float bv = bt[clampi(jk - jq + 15, 0, 30)]; const float xv = ok ? (S[c][kt][r] + bv) : -1e30f; S[c][kt][r] = xv; mx = fmaxf(mx, xv); }
;                 } else {
; #pragma unroll
;                     for (int kt = 0; kt < 2; ++kt)
; #pragma unroll
;                         for (int r = 0; r < 16; r += 2) mx = fmaxf(fmaxf(mx, S[c][kt][r]), S[c][kt][r + 1]);
;                 }
;                 mxc[c] = mx;
;             }
; #pragma unroll
;             for (int c = 0; c < NCOMP; ++c) mxc[c] = fmaxf(mxc[c], shflx(mxc[c], 32));
.LBB0_269:
	ds_read_b128 v[72:75], v239
	ds_read_b128 v[76:79], v239 offset:32
	ds_read_b128 v[80:83], v239 offset:4608
	ds_read_b128 v[222:225], v239 offset:4640
	ds_read_b128 v[226:229], v239 offset:64
	ds_read_b128 v[246:249], v239 offset:96
	ds_read_b128 v[68:71], v239 offset:4672
	ds_read_b128 v[190:193], v239 offset:4704
.Ldiff_mfma:
	s_xor_b64 s[14:15], s[12:13], -1
	s_setprio 1
	s_waitcnt lgkmcnt(7)
	v_mfma_f32_32x32x16_bf16 v[116:131], v[72:75], v[148:151], 0
	s_waitcnt lgkmcnt(6)
	v_mfma_f32_32x32x16_bf16 v[116:131], v[76:79], v[156:159], v[116:131]
	s_waitcnt lgkmcnt(5)
	v_mfma_f32_32x32x16_bf16 v[100:115], v[80:83], v[148:151], 0
	s_waitcnt lgkmcnt(4)
	v_mfma_f32_32x32x16_bf16 v[100:115], v[222:225], v[156:159], v[100:115]
	s_waitcnt lgkmcnt(3)
	v_mfma_f32_32x32x16_bf16 v[84:99], v[226:229], v[160:163], 0
	s_waitcnt lgkmcnt(2)
	v_mfma_f32_32x32x16_bf16 v[84:99], v[246:249], v[168:171], v[84:99]
	s_waitcnt lgkmcnt(1)
	v_mfma_f32_32x32x16_bf16 v[68:83], v[68:71], v[160:163], 0
	s_waitcnt lgkmcnt(0)
	v_mfma_f32_32x32x16_bf16 v[68:83], v[190:193], v[168:171], v[68:83]
	s_setprio 0
	s_and_b64 vcc, exec, s[14:15]
	s_cbranch_vccnz .LBB0_281
	s_nop 0
	v_max3_f32 v2, v84, s33, v85
	v_max3_f32 v2, v2, v86, v87
	v_max3_f32 v2, v2, v88, v89
	v_max3_f32 v1, v116, s33, v117
	v_max3_f32 v2, v2, v90, v91
	v_max3_f32 v1, v1, v118, v119
	v_max3_f32 v2, v2, v92, v93
	v_max3_f32 v1, v1, v120, v121
	v_max3_f32 v2, v2, v94, v95
	v_max3_f32 v1, v1, v122, v123
	v_max3_f32 v2, v2, v96, v97
	v_max3_f32 v1, v1, v124, v125
	v_max3_f32 v2, v2, v98, v99
	v_max3_f32 v1, v1, v126, v127
	v_max3_f32 v2, v2, v68, v69
	v_max3_f32 v1, v1, v128, v129
	v_max3_f32 v2, v2, v70, v71
	v_max3_f32 v1, v1, v130, v131
	v_max3_f32 v2, v2, v72, v73
	v_max3_f32 v1, v1, v100, v101
	v_max3_f32 v2, v2, v74, v75
	v_max3_f32 v1, v1, v102, v103
	v_max3_f32 v2, v2, v76, v77
	v_max3_f32 v1, v1, v104, v105
	v_max3_f32 v2, v2, v78, v79
	v_max3_f32 v1, v1, v106, v107
	v_max3_f32 v2, v2, v80, v81
	v_max3_f32 v1, v1, v108, v109
	v_max3_f32 v3, v2, v82, v83
	v_mov_b32_e32 v2, v220
	v_mov_b32_e32 v190, v220
	v_max3_f32 v1, v1, v110, v111
	v_max3_f32 v1, v1, v112, v113
	v_lshlrev_b32_e32 v2, 2, v2
	v_lshlrev_b32_e32 v190, 2, v190
	v_max3_f32 v1, v1, v114, v115
	v_xor_b32_e32 v2, 0x80, v2
	v_xor_b32_e32 v190, 0x80, v190
	ds_bpermute_b32 v2, v2, v1
	ds_bpermute_b32 v190, v190, v3
	s_andn2_b64 vcc, exec, s[10:11]
	s_mov_b64 s[2:3], 0
	s_waitcnt lgkmcnt(1)
	v_max3_f32 v2, v240, v1, v2
	s_waitcnt lgkmcnt(0)
	v_max3_f32 v1, v238, v3, v190
	s_cbranch_vccnz .LBB0_272
	v_cmp_nlt_f32_e64 s[0:1], |v2|, s53
	v_cmp_nlt_f32_e64 s[2:3], |v1|, s53
	s_or_b64 s[0:1], s[0:1], s[2:3]
	v_cndmask_b32_e64 v3, 0, 1, s[0:1]
	v_cmp_ne_u32_e32 vcc, 0, v3
	s_cmp_eq_u64 vcc, 0
	s_cselect_b64 s[2:3], -1, 0

; #define STORE_TILE(buf) do { LAS unsigned char* _kb = lds + (buf) * BUFSZ; *(LAS u32x4*)(_kb + kr0 * KSTR + kc0 * 16) = rk0; \
;         if (hask1) *(LAS u32x4*)(_kb + kr1 * KSTR + kc1 * 16) = rk1; *(LAS u32x4*)(_kb + KBUF + vr * VSTR + vc * 16) = rv; } while (0)
; template <int MODE>
; __device__ __forceinline__ void attn_item(PK p, int l, LAS unsigned char* lds, int b, int h, int qb, bool ctxq, float lam, float lam_init) {
;     ...
;         const int nbuf = (cbuf == 2) ? 0 : cbuf + 1;
;         if (more) STORE_TILE(nbuf);
;         __syncthreads();
;         cbuf = nbuf;
;     }
.LBB0_282:
	s_add_i32 s0, s17, 1
	s_cmp_lg_u32 s17, 2
	s_cselect_b32 s17, s0, 0
.LBB0_284:
	s_cmpk_lg_i32 s18, 0x84
	s_waitcnt lgkmcnt(0)
	s_barrier
	s_cbranch_scc0 .LBB0_54
	s_mov_b32 s0, s18
	s_branch .LBB0_265
